# pool mixer: each row's output store is issued after the next row's window loads, so the load wait (vmcnt(1)) no longer waits on the store acknowledgement
# baseline (speedup 1.0000x reference)
; __device__ __forceinline__ unsigned cvt_pk_bf16(float lo, float hi) { unsigned r; asm volatile("v_cvt_pk_bf16_f32 %0, %1, %2" : "=v"(r) : "v"(lo), "v"(hi)); return r; }
; __device__ __forceinline__ float bf_lo(unsigned w) { return __uint_as_float(w << 16); }
; __device__ __forceinline__ float bf_hi(unsigned w) { return __uint_as_float(w & 0xffff0000u); }
; __device__ __forceinline__ void pool_phase(const bf16_t* ZP, bf16_t* CAT, int gw, int NGW, int lane) {
;     const int gi = lane >> 4, w = 2 << gi, lo = w >> 1, hi = w - 1 - lo;
;     for (int row = gw; row < MTOK; row += NGW) {
;         const int tl = row & (SEQL - 1); float acc[8];
; #pragma unroll
;         for (int j = 0; j < 8; ++j) acc[j] = 0.f;
;         const int d0 = -min(lo, tl), d1 = min(hi, SEQL - 1 - tl);
; #pragma unroll
;         for (int d = -8; d <= 7; ++d) if (d >= d0 && d <= d1) { const u32x4 z = *(const u32x4*)(ZP + (size_t)(row + d) * 512 + lane * 8);
;             acc[0] += bf_lo(z.x); acc[1] += bf_hi(z.x); acc[2] += bf_lo(z.y); acc[3] += bf_hi(z.y); acc[4] += bf_lo(z.z); acc[5] += bf_hi(z.z); acc[6] += bf_lo(z.w); acc[7] += bf_hi(z.w); }
;         const float inv = 1.0f / (float)(d1 - d0 + 1); const u32x4 z = *(const u32x4*)(ZP + (size_t)row * 512 + lane * 8);
;         u32x4 o; o.x = cvt_pk_bf16(acc[0] * inv - bf_lo(z.x), acc[1] * inv - bf_hi(z.x)); o.y = cvt_pk_bf16(acc[2] * inv - bf_lo(z.y), acc[3] * inv - bf_hi(z.y));
;         o.z = cvt_pk_bf16(acc[4] * inv - bf_lo(z.z), acc[5] * inv - bf_hi(z.z)); o.w = cvt_pk_bf16(acc[6] * inv - bf_lo(z.w), acc[7] * inv - bf_hi(z.w));
;         *(u32x4*)(CAT + (size_t)row * 1024 + lane * 8) = o;
.LBB0_860:
	s_cmp_ge_i32 s26, s86
	s_cselect_b64 s[28:29], -1, 0
	s_and_b64 s[0:1], s[28:29], s[0:1]
	s_andn2_b64 vcc, exec, s[0:1]
	s_cbranch_vccnz .LBB0_877
	v_readfirstlane_b32 s8, v202
	s_nop 3
	s_ashr_i32 s0, s8, 6
	s_cmp_lt_u32 s0, 2
	s_cbranch_scc1 .Lc_nopool
	s_load_dwordx4 s[44:47], s[82:83], 0xb0
	s_add_i32 s0, s0, -2
	s_mul_i32 s1, s2, 6
	s_add_i32 s8, s0, s1
	s_waitcnt lgkmcnt(0)
	s_add_u32 s12, s46, 0x8000000
	s_addc_u32 s13, s47, 0
	s_mov_b32 s0, s8
	s_mov_b32 s1, 0
	s_lshl_b64 s[14:15], s[0:1], 11
	s_add_u32 s14, s44, s14
	s_addc_u32 s15, s45, s15
	s_lshl_b64 s[0:1], s[0:1], 10
	s_add_u32 s0, s12, s0
	s_addc_u32 s1, s13, s1
	v_and_b32_e32 v2, 63, v202
	v_bfe_u32 v0, v202, 4, 2
	v_lshlrev_b32_e64 v0, v0, 2
	v_lshrrev_b32_e32 v18, 1, v0
	v_xad_u32 v19, v18, -1, v0
	v_lshlrev_b32_e32 v0, 4, v2
	v_lshl_add_u64 v[2:3], s[12:13], 0, v[0:1]
	v_lshl_add_u64 v[4:5], s[14:15], 0, v[0:1]
	v_lshl_add_u64 v[6:7], s[0:1], 0, v[0:1]
	s_mov_b32 s13, 0
	s_branch .LBB0_740
.LBB0_739:
	s_or_b64 exec, exec, s[0:1]
	v_add3_u32 v0, v0, v16, 1
	v_cvt_f32_i32_e32 v0, v0
	s_add_i32 s8, s8, 0x600
	s_cmp_lt_i32 s8, 0x10000
	v_div_scale_f32 v16, s[0:1], v0, v0, 1.0
	v_rcp_f32_e32 v17, v16
	v_div_scale_f32 v24, vcc, 1.0, v0, 1.0
	v_fma_f32 v25, -v16, v17, 1.0
	v_fmac_f32_e32 v17, v25, v17
	v_mul_f32_e32 v25, v24, v17
	v_fma_f32 v26, -v16, v25, v24
	v_fmac_f32_e32 v25, v26, v17
	v_fma_f32 v16, -v16, v25, v24
	v_div_fmas_f32 v16, v16, v17, v25
	v_div_fixup_f32 v0, v16, v0, 1.0
	s_mov_b64 s[0:1], 0x300000
	v_lshlrev_b32_e32 v16, 16, v162
	v_and_b32_e32 v17, 0xffff0000, v162
	v_lshlrev_b32_e32 v20, 16, v163
	v_and_b32_e32 v21, 0xffff0000, v163
	v_lshlrev_b32_e32 v24, 16, v164
	v_and_b32_e32 v22, 0xffff0000, v164
	v_lshlrev_b32_e32 v25, 16, v165
	v_and_b32_e32 v23, 0xffff0000, v165
	v_fma_f32 v8, v0, v8, -v16
	v_fma_f32 v9, v0, v9, -v17
	v_fma_f32 v10, v0, v10, -v20
	v_fma_f32 v11, v0, v11, -v21
	v_fma_f32 v12, v0, v12, -v24
	v_fma_f32 v13, v0, v13, -v22
	v_fma_f32 v14, v0, v14, -v25
	v_fma_f32 v0, v0, v15, -v23
	v_cvt_pk_bf16_f32 v8, v8, v9
	v_cvt_pk_bf16_f32 v9, v10, v11
	v_cvt_pk_bf16_f32 v10, v12, v13
	v_cvt_pk_bf16_f32 v11, v14, v0
	v_mov_b32_e32 v26, v4
	v_mov_b32_e32 v27, v5
	s_mov_b32 s13, 1
	v_lshl_add_u64 v[4:5], v[4:5], 0, s[0:1]
	s_mov_b64 s[0:1], 0x180000
	s_nop 1
	v_lshl_add_u64 v[6:7], v[6:7], 0, s[0:1]
	s_cbranch_scc0 .Lc_poolfin
.LBB0_740:
	s_and_b32 s9, s8, 0x1fff
	v_min_i32_e32 v0, s9, v18
	s_xor_b32 s0, s9, 0x1fff
	v_min_i32_e32 v16, s0, v19
	v_mov_b64_e32 v[130:131], 0
	v_mov_b64_e32 v[132:133], 0
	v_mov_b64_e32 v[134:135], 0
	v_mov_b64_e32 v[136:137], 0
	v_mov_b64_e32 v[138:139], 0
	v_mov_b64_e32 v[140:141], 0
	v_mov_b64_e32 v[142:143], 0
	v_mov_b64_e32 v[144:145], 0
	v_mov_b64_e32 v[146:147], 0
	v_mov_b64_e32 v[148:149], 0
	v_mov_b64_e32 v[150:151], 0
	v_mov_b64_e32 v[152:153], 0
	v_mov_b64_e32 v[154:155], 0
	v_mov_b64_e32 v[156:157], 0
	v_mov_b64_e32 v[158:159], 0
	v_mov_b64_e32 v[160:161], 0
	v_mov_b64_e32 v[162:163], 0
	v_mov_b64_e32 v[164:165], 0
	v_mov_b64_e32 v[166:167], 0
	v_mov_b64_e32 v[168:169], 0
	v_mov_b64_e32 v[170:171], 0
	v_mov_b64_e32 v[172:173], 0
	v_mov_b64_e32 v[174:175], 0
	v_mov_b64_e32 v[176:177], 0
	v_mov_b64_e32 v[178:179], 0
	v_mov_b64_e32 v[180:181], 0
	v_mov_b64_e32 v[182:183], 0
	v_mov_b64_e32 v[184:185], 0
	v_mov_b64_e32 v[186:187], 0
	v_mov_b64_e32 v[188:189], 0
	v_mov_b64_e32 v[190:191], 0
	v_mov_b64_e32 v[192:193], 0
	v_add_co_u32_e32 v196, vcc, 0xffffe000, v6
	s_nop 1
	v_addc_co_u32_e32 v197, vcc, -1, v7, vcc
	v_add_co_u32_e32 v198, vcc, 0xfffff000, v6
	s_nop 1
	v_addc_co_u32_e32 v199, vcc, -1, v7, vcc
	v_add_co_u32_e32 v200, vcc, 0x1000, v6
	s_nop 1
	v_addc_co_u32_e32 v201, vcc, 0, v7, vcc
	s_mov_b64 s[0:1], exec
	v_cmp_lt_u32_e32 vcc, 7, v0
	s_and_b64 exec, s[0:1], vcc
	global_load_dwordx4 v[130:133], v[196:197], off
	s_mov_b64 exec, s[0:1]
	v_cmp_lt_u32_e32 vcc, 6, v0
	s_and_b64 exec, s[0:1], vcc
	global_load_dwordx4 v[134:137], v[196:197], off offset:1024
	s_mov_b64 exec, s[0:1]
	v_cmp_lt_u32_e32 vcc, 5, v0
	s_and_b64 exec, s[0:1], vcc
	global_load_dwordx4 v[138:141], v[196:197], off offset:2048
	s_mov_b64 exec, s[0:1]
	v_cmp_lt_u32_e32 vcc, 4, v0
	s_and_b64 exec, s[0:1], vcc
	global_load_dwordx4 v[142:145], v[196:197], off offset:3072
	s_mov_b64 exec, s[0:1]
	v_cmp_lt_u32_e32 vcc, 3, v0
	s_and_b64 exec, s[0:1], vcc
	global_load_dwordx4 v[146:149], v[198:199], off
	s_mov_b64 exec, s[0:1]
	v_cmp_lt_u32_e32 vcc, 2, v0
	s_and_b64 exec, s[0:1], vcc
	global_load_dwordx4 v[150:153], v[198:199], off offset:1024
	s_mov_b64 exec, s[0:1]
	v_cmp_lt_u32_e32 vcc, 1, v0
	s_and_b64 exec, s[0:1], vcc
	global_load_dwordx4 v[154:157], v[198:199], off offset:2048
	s_mov_b64 exec, s[0:1]
	v_cmp_lt_u32_e32 vcc, 0, v0
	s_and_b64 exec, s[0:1], vcc
	global_load_dwordx4 v[158:161], v[198:199], off offset:3072
	s_mov_b64 exec, s[0:1]
	global_load_dwordx4 v[162:165], v[6:7], off
	v_cmp_le_i32_e32 vcc, 1, v16
	s_and_b64 exec, s[0:1], vcc
	global_load_dwordx4 v[166:169], v[6:7], off offset:1024
	s_mov_b64 exec, s[0:1]
	v_cmp_le_i32_e32 vcc, 2, v16
	s_and_b64 exec, s[0:1], vcc
	global_load_dwordx4 v[170:173], v[6:7], off offset:2048
	s_mov_b64 exec, s[0:1]
	v_cmp_le_i32_e32 vcc, 3, v16
	s_and_b64 exec, s[0:1], vcc
	global_load_dwordx4 v[174:177], v[6:7], off offset:3072
	s_mov_b64 exec, s[0:1]
	v_cmp_le_i32_e32 vcc, 4, v16
	s_and_b64 exec, s[0:1], vcc
	global_load_dwordx4 v[178:181], v[200:201], off
	s_mov_b64 exec, s[0:1]
	v_cmp_le_i32_e32 vcc, 5, v16
	s_and_b64 exec, s[0:1], vcc
	global_load_dwordx4 v[182:185], v[200:201], off offset:1024
	s_mov_b64 exec, s[0:1]
	v_cmp_le_i32_e32 vcc, 6, v16
	s_and_b64 exec, s[0:1], vcc
	global_load_dwordx4 v[186:189], v[200:201], off offset:2048
	s_mov_b64 exec, s[0:1]
	v_cmp_le_i32_e32 vcc, 7, v16
	s_and_b64 exec, s[0:1], vcc
	global_load_dwordx4 v[190:193], v[200:201], off offset:3072
	s_mov_b64 exec, s[0:1]
	s_cmp_eq_u32 s13, 0
	s_cbranch_scc1 .Lcp_first
	global_store_dwordx4 v[26:27], v[8:11], off
	s_waitcnt vmcnt(1)
	s_branch .Lcp_go

; __device__ __forceinline__ float bf_lo(unsigned w) { return __uint_as_float(w << 16); }
; __device__ __forceinline__ float bf_hi(unsigned w) { return __uint_as_float(w & 0xffff0000u); }
; __device__ __forceinline__ void pool_phase(const bf16_t* ZP, bf16_t* CAT, int gw, int NGW, int lane) {
;     ...
; #pragma unroll
;         for (int d = -8; d <= 7; ++d) if (d >= d0 && d <= d1) { const u32x4 z = *(const u32x4*)(ZP + (size_t)(row + d) * 512 + lane * 8);
;             acc[0] += bf_lo(z.x); acc[1] += bf_hi(z.x); acc[2] += bf_lo(z.y); acc[3] += bf_hi(z.y); acc[4] += bf_lo(z.z); acc[5] += bf_hi(z.z); acc[6] += bf_lo(z.w); acc[7] += bf_hi(z.w); }
.Lcp_go:
	v_lshlrev_b32_e32 v20, 16, v130
	v_and_b32_e32 v21, 0xffff0000, v130
	v_lshlrev_b32_e32 v22, 16, v131
	v_and_b32_e32 v23, 0xffff0000, v131
	v_lshlrev_b32_e32 v24, 16, v132
	v_and_b32_e32 v25, 0xffff0000, v132
	v_lshlrev_b32_e32 v194, 16, v133
	v_and_b32_e32 v195, 0xffff0000, v133
	v_pk_add_f32 v[8:9], v[20:21], 0 op_sel_hi:[1,0]
	v_pk_add_f32 v[10:11], v[22:23], 0 op_sel_hi:[1,0]
	v_pk_add_f32 v[12:13], v[24:25], 0 op_sel_hi:[1,0]
	v_pk_add_f32 v[14:15], v[194:195], 0 op_sel_hi:[1,0]
	v_lshlrev_b32_e32 v20, 16, v134
	v_and_b32_e32 v21, 0xffff0000, v134
	v_lshlrev_b32_e32 v22, 16, v135
	v_and_b32_e32 v23, 0xffff0000, v135
	v_lshlrev_b32_e32 v24, 16, v136
	v_and_b32_e32 v25, 0xffff0000, v136
	v_lshlrev_b32_e32 v194, 16, v137
	v_and_b32_e32 v195, 0xffff0000, v137
	v_pk_add_f32 v[8:9], v[8:9], v[20:21]
	v_pk_add_f32 v[10:11], v[10:11], v[22:23]
	v_pk_add_f32 v[12:13], v[12:13], v[24:25]
	v_pk_add_f32 v[14:15], v[14:15], v[194:195]
	v_lshlrev_b32_e32 v20, 16, v138
	v_and_b32_e32 v21, 0xffff0000, v138
	v_lshlrev_b32_e32 v22, 16, v139
	v_and_b32_e32 v23, 0xffff0000, v139
	v_lshlrev_b32_e32 v24, 16, v140
	v_and_b32_e32 v25, 0xffff0000, v140
	v_lshlrev_b32_e32 v194, 16, v141
	v_and_b32_e32 v195, 0xffff0000, v141
	v_pk_add_f32 v[8:9], v[8:9], v[20:21]
	v_pk_add_f32 v[10:11], v[10:11], v[22:23]
	v_pk_add_f32 v[12:13], v[12:13], v[24:25]
	v_pk_add_f32 v[14:15], v[14:15], v[194:195]
	v_lshlrev_b32_e32 v20, 16, v142
	v_and_b32_e32 v21, 0xffff0000, v142
	v_lshlrev_b32_e32 v22, 16, v143
	v_and_b32_e32 v23, 0xffff0000, v143
	v_lshlrev_b32_e32 v24, 16, v144
	v_and_b32_e32 v25, 0xffff0000, v144
	v_lshlrev_b32_e32 v194, 16, v145
	v_and_b32_e32 v195, 0xffff0000, v145
	v_pk_add_f32 v[8:9], v[8:9], v[20:21]
	v_pk_add_f32 v[10:11], v[10:11], v[22:23]
	v_pk_add_f32 v[12:13], v[12:13], v[24:25]
	v_pk_add_f32 v[14:15], v[14:15], v[194:195]
	v_lshlrev_b32_e32 v20, 16, v146
	v_and_b32_e32 v21, 0xffff0000, v146
	v_lshlrev_b32_e32 v22, 16, v147
	v_and_b32_e32 v23, 0xffff0000, v147
	v_lshlrev_b32_e32 v24, 16, v148
	v_and_b32_e32 v25, 0xffff0000, v148
	v_lshlrev_b32_e32 v194, 16, v149
	v_and_b32_e32 v195, 0xffff0000, v149
	v_pk_add_f32 v[8:9], v[8:9], v[20:21]
	v_pk_add_f32 v[10:11], v[10:11], v[22:23]
	v_pk_add_f32 v[12:13], v[12:13], v[24:25]
	v_pk_add_f32 v[14:15], v[14:15], v[194:195]
	v_lshlrev_b32_e32 v20, 16, v150
	v_and_b32_e32 v21, 0xffff0000, v150
	v_lshlrev_b32_e32 v22, 16, v151
	v_and_b32_e32 v23, 0xffff0000, v151
	v_lshlrev_b32_e32 v24, 16, v152
	v_and_b32_e32 v25, 0xffff0000, v152
	v_lshlrev_b32_e32 v194, 16, v153
	v_and_b32_e32 v195, 0xffff0000, v153
	v_pk_add_f32 v[8:9], v[8:9], v[20:21]
	v_pk_add_f32 v[10:11], v[10:11], v[22:23]
	v_pk_add_f32 v[12:13], v[12:13], v[24:25]
	v_pk_add_f32 v[14:15], v[14:15], v[194:195]
	v_lshlrev_b32_e32 v20, 16, v154
	v_and_b32_e32 v21, 0xffff0000, v154
	v_lshlrev_b32_e32 v22, 16, v155
	v_and_b32_e32 v23, 0xffff0000, v155
	v_lshlrev_b32_e32 v24, 16, v156
	v_and_b32_e32 v25, 0xffff0000, v156
	v_lshlrev_b32_e32 v194, 16, v157
	v_and_b32_e32 v195, 0xffff0000, v157
	v_pk_add_f32 v[8:9], v[8:9], v[20:21]
	v_pk_add_f32 v[10:11], v[10:11], v[22:23]
	v_pk_add_f32 v[12:13], v[12:13], v[24:25]
	v_pk_add_f32 v[14:15], v[14:15], v[194:195]
	v_lshlrev_b32_e32 v20, 16, v158
	v_and_b32_e32 v21, 0xffff0000, v158
	v_lshlrev_b32_e32 v22, 16, v159
	v_and_b32_e32 v23, 0xffff0000, v159
	v_lshlrev_b32_e32 v24, 16, v160
	v_and_b32_e32 v25, 0xffff0000, v160
	v_lshlrev_b32_e32 v194, 16, v161
	v_and_b32_e32 v195, 0xffff0000, v161
	v_pk_add_f32 v[8:9], v[8:9], v[20:21]
	v_pk_add_f32 v[10:11], v[10:11], v[22:23]
	v_pk_add_f32 v[12:13], v[12:13], v[24:25]
	v_pk_add_f32 v[14:15], v[14:15], v[194:195]
; __device__ __forceinline__ unsigned cvt_pk_bf16(float lo, float hi) { unsigned r; asm volatile("v_cvt_pk_bf16_f32 %0, %1, %2" : "=v"(r) : "v"(lo), "v"(hi)); return r; }
; __device__ __forceinline__ float bf_lo(unsigned w) { return __uint_as_float(w << 16); }
; __device__ __forceinline__ float bf_hi(unsigned w) { return __uint_as_float(w & 0xffff0000u); }
; __device__ __forceinline__ void pool_phase(const bf16_t* ZP, bf16_t* CAT, int gw, int NGW, int lane) {
;     ...
; #pragma unroll
;         for (int d = -8; d <= 7; ++d) if (d >= d0 && d <= d1) { const u32x4 z = *(const u32x4*)(ZP + (size_t)(row + d) * 512 + lane * 8);
;             acc[0] += bf_lo(z.x); acc[1] += bf_hi(z.x); acc[2] += bf_lo(z.y); acc[3] += bf_hi(z.y); acc[4] += bf_lo(z.z); acc[5] += bf_hi(z.z); acc[6] += bf_lo(z.w); acc[7] += bf_hi(z.w); }
;         const float inv = 1.0f / (float)(d1 - d0 + 1); const u32x4 z = *(const u32x4*)(ZP + (size_t)row * 512 + lane * 8);
;         u32x4 o; o.x = cvt_pk_bf16(acc[0] * inv - bf_lo(z.x), acc[1] * inv - bf_hi(z.x)); o.y = cvt_pk_bf16(acc[2] * inv - bf_lo(z.y), acc[3] * inv - bf_hi(z.y));
;         o.z = cvt_pk_bf16(acc[4] * inv - bf_lo(z.z), acc[5] * inv - bf_hi(z.z)); o.w = cvt_pk_bf16(acc[6] * inv - bf_lo(z.w), acc[7] * inv - bf_hi(z.w));
;         *(u32x4*)(CAT + (size_t)row * 1024 + lane * 8) = o;
	v_lshlrev_b32_e32 v20, 16, v162
	v_and_b32_e32 v21, 0xffff0000, v162
	v_lshlrev_b32_e32 v22, 16, v163
	v_and_b32_e32 v23, 0xffff0000, v163
	v_lshlrev_b32_e32 v24, 16, v164
	v_and_b32_e32 v25, 0xffff0000, v164
	v_lshlrev_b32_e32 v194, 16, v165
	v_and_b32_e32 v195, 0xffff0000, v165
	v_pk_add_f32 v[8:9], v[8:9], v[20:21]
	v_pk_add_f32 v[10:11], v[10:11], v[22:23]
	v_pk_add_f32 v[12:13], v[12:13], v[24:25]
	v_pk_add_f32 v[14:15], v[14:15], v[194:195]
	v_lshlrev_b32_e32 v20, 16, v166
	v_and_b32_e32 v21, 0xffff0000, v166
	v_lshlrev_b32_e32 v22, 16, v167
	v_and_b32_e32 v23, 0xffff0000, v167
	v_lshlrev_b32_e32 v24, 16, v168
	v_and_b32_e32 v25, 0xffff0000, v168
	v_lshlrev_b32_e32 v194, 16, v169
	v_and_b32_e32 v195, 0xffff0000, v169
	v_pk_add_f32 v[8:9], v[8:9], v[20:21]
	v_pk_add_f32 v[10:11], v[10:11], v[22:23]
	v_pk_add_f32 v[12:13], v[12:13], v[24:25]
	v_pk_add_f32 v[14:15], v[14:15], v[194:195]
	v_lshlrev_b32_e32 v20, 16, v170
	v_and_b32_e32 v21, 0xffff0000, v170
	v_lshlrev_b32_e32 v22, 16, v171
	v_and_b32_e32 v23, 0xffff0000, v171
	v_lshlrev_b32_e32 v24, 16, v172
	v_and_b32_e32 v25, 0xffff0000, v172
	v_lshlrev_b32_e32 v194, 16, v173
	v_and_b32_e32 v195, 0xffff0000, v173
	v_pk_add_f32 v[8:9], v[8:9], v[20:21]
	v_pk_add_f32 v[10:11], v[10:11], v[22:23]
	v_pk_add_f32 v[12:13], v[12:13], v[24:25]
	v_pk_add_f32 v[14:15], v[14:15], v[194:195]
	v_lshlrev_b32_e32 v20, 16, v174
	v_and_b32_e32 v21, 0xffff0000, v174
	v_lshlrev_b32_e32 v22, 16, v175
	v_and_b32_e32 v23, 0xffff0000, v175
	v_lshlrev_b32_e32 v24, 16, v176
	v_and_b32_e32 v25, 0xffff0000, v176
	v_lshlrev_b32_e32 v194, 16, v177
	v_and_b32_e32 v195, 0xffff0000, v177
	v_pk_add_f32 v[8:9], v[8:9], v[20:21]
	v_pk_add_f32 v[10:11], v[10:11], v[22:23]
	v_pk_add_f32 v[12:13], v[12:13], v[24:25]
	v_pk_add_f32 v[14:15], v[14:15], v[194:195]
	v_lshlrev_b32_e32 v20, 16, v178
	v_and_b32_e32 v21, 0xffff0000, v178
	v_lshlrev_b32_e32 v22, 16, v179
	v_and_b32_e32 v23, 0xffff0000, v179
	v_lshlrev_b32_e32 v24, 16, v180
	v_and_b32_e32 v25, 0xffff0000, v180
	v_lshlrev_b32_e32 v194, 16, v181
	v_and_b32_e32 v195, 0xffff0000, v181
	v_pk_add_f32 v[8:9], v[8:9], v[20:21]
	v_pk_add_f32 v[10:11], v[10:11], v[22:23]
	v_pk_add_f32 v[12:13], v[12:13], v[24:25]
	v_pk_add_f32 v[14:15], v[14:15], v[194:195]
	v_lshlrev_b32_e32 v20, 16, v182
	v_and_b32_e32 v21, 0xffff0000, v182
	v_lshlrev_b32_e32 v22, 16, v183
	v_and_b32_e32 v23, 0xffff0000, v183
	v_lshlrev_b32_e32 v24, 16, v184
	v_and_b32_e32 v25, 0xffff0000, v184
	v_lshlrev_b32_e32 v194, 16, v185
	v_and_b32_e32 v195, 0xffff0000, v185
	v_pk_add_f32 v[8:9], v[8:9], v[20:21]
	v_pk_add_f32 v[10:11], v[10:11], v[22:23]
	v_pk_add_f32 v[12:13], v[12:13], v[24:25]
	v_pk_add_f32 v[14:15], v[14:15], v[194:195]
	v_lshlrev_b32_e32 v20, 16, v186
	v_and_b32_e32 v21, 0xffff0000, v186
	v_lshlrev_b32_e32 v22, 16, v187
	v_and_b32_e32 v23, 0xffff0000, v187
	v_lshlrev_b32_e32 v24, 16, v188
	v_and_b32_e32 v25, 0xffff0000, v188
	v_lshlrev_b32_e32 v194, 16, v189
	v_and_b32_e32 v195, 0xffff0000, v189
	v_pk_add_f32 v[8:9], v[8:9], v[20:21]
	v_pk_add_f32 v[10:11], v[10:11], v[22:23]
	v_pk_add_f32 v[12:13], v[12:13], v[24:25]
	v_pk_add_f32 v[14:15], v[14:15], v[194:195]
	v_lshlrev_b32_e32 v20, 16, v190
	v_and_b32_e32 v21, 0xffff0000, v190
	v_lshlrev_b32_e32 v22, 16, v191
	v_and_b32_e32 v23, 0xffff0000, v191
	v_lshlrev_b32_e32 v24, 16, v192
	v_and_b32_e32 v25, 0xffff0000, v192
	v_lshlrev_b32_e32 v194, 16, v193
	v_and_b32_e32 v195, 0xffff0000, v193
	v_pk_add_f32 v[8:9], v[8:9], v[20:21]
	v_pk_add_f32 v[10:11], v[10:11], v[22:23]
	v_pk_add_f32 v[12:13], v[12:13], v[24:25]
	v_pk_add_f32 v[14:15], v[14:15], v[194:195]
	s_branch .LBB0_739
.Lc_poolfin:
	global_store_dwordx4 v[26:27], v[8:11], off
